# attention steady loop: QK MFMAs reordered C0 x4 then C1 x4 so half of the row-max reduction runs in the MFMA shadow; exposed max chain shrinks from 17 to 10 VALU
# baseline (speedup 1.0000x reference)
.LBB0_1277:
	s_lshl_b32 s18, s23, 1
	v_mfma_f32_32x32x16_bf16 v[112:127], v[188:191], v[156:159], v[238:253]
	v_add_u32_e32 v237, s18, v214
	ds_read_b64_tr_b16 v[192:193], v237 offset:24576
	v_add_f32_e32 v128, v80, v81
	v_add_f32_e32 v128, v82, v128
	v_add_f32_e32 v128, v83, v128
	v_add_f32_e32 v128, v84, v128
	v_add_f32_e32 v128, v85, v128
	v_cvt_pk_bf16_f32 v148, v80, v81
	v_cvt_pk_bf16_f32 v149, v82, v83
	ds_read_b64_tr_b16 v[194:195], v237 offset:25088
	s_waitcnt lgkmcnt(8)
	v_mfma_f32_32x32x16_bf16 v[112:127], v[180:183], v[152:155], v[112:127]
	v_add_f32_e32 v80, v86, v128
	v_add_f32_e32 v80, v87, v80
	v_add_f32_e32 v80, v88, v80
	v_add_f32_e32 v82, v89, v80
	v_cvt_pk_bf16_f32 v150, v84, v85
	v_cvt_pk_bf16_f32 v151, v86, v87
	ds_read_b64_tr_b16 v[80:81], v237 offset:28672
	s_waitcnt lgkmcnt(8)
	v_mfma_f32_32x32x16_bf16 v[112:127], v[172:175], v[144:147], v[112:127]
	v_add_f32_e32 v82, v90, v82
	v_add_f32_e32 v82, v91, v82
	v_add_f32_e32 v82, v92, v82
	v_add_f32_e32 v84, v93, v82
	v_cvt_pk_bf16_f32 v140, v88, v89
	v_cvt_pk_bf16_f32 v141, v90, v91
	ds_read_b64_tr_b16 v[82:83], v237 offset:29184
	s_waitcnt lgkmcnt(8)
	v_mfma_f32_32x32x16_bf16 v[112:127], v[164:167], v[136:139], v[112:127]
	v_add_f32_e32 v84, v94, v84
	v_add_f32_e32 v84, v95, v84
	v_add_f32_e32 v84, v64, v84
	v_add_f32_e32 v86, v65, v84
	v_cvt_pk_bf16_f32 v142, v92, v93
	v_cvt_pk_bf16_f32 v143, v94, v95
	ds_read_b64_tr_b16 v[84:85], v237 offset:32768
	s_waitcnt lgkmcnt(8)
	v_mfma_f32_32x32x16_bf16 v[96:111], v[184:187], v[156:159], v[238:253]
	v_add_f32_e32 v86, v66, v86
	v_add_f32_e32 v86, v67, v86
	v_add_f32_e32 v86, v68, v86
	v_add_f32_e32 v88, v69, v86
	v_cvt_pk_bf16_f32 v132, v64, v65
	v_cvt_pk_bf16_f32 v133, v66, v67
	ds_read_b64_tr_b16 v[86:87], v237 offset:33280
	s_waitcnt lgkmcnt(8)
	v_mfma_f32_32x32x16_bf16 v[96:111], v[176:179], v[152:155], v[96:111]
	v_add_f32_e32 v64, v70, v88
	v_add_f32_e32 v64, v71, v64
	v_add_f32_e32 v64, v72, v64
	v_add_f32_e32 v66, v73, v64
	v_cvt_pk_bf16_f32 v134, v68, v69
	v_cvt_pk_bf16_f32 v135, v70, v71
	ds_read_b64_tr_b16 v[64:65], v237 offset:36864
	s_waitcnt lgkmcnt(8)
	v_mfma_f32_32x32x16_bf16 v[96:111], v[168:171], v[144:147], v[96:111]
	v_add_f32_e32 v66, v74, v66
	v_add_f32_e32 v66, v75, v66
	v_add_f32_e32 v66, v76, v66
	v_add_f32_e32 v68, v77, v66
	v_cvt_pk_bf16_f32 v128, v72, v73
	v_cvt_pk_bf16_f32 v129, v74, v75
	v_max_f32_e32 v69, v112, v113
	v_max3_f32 v69, v69, v114, v115
	v_max3_f32 v69, v69, v116, v117
	v_max3_f32 v69, v69, v118, v119
	ds_read_b64_tr_b16 v[66:67], v237 offset:37376
	s_waitcnt lgkmcnt(8)
	v_mfma_f32_32x32x16_bf16 v[96:111], v[160:163], v[136:139], v[96:111]
	v_add_f32_e32 v68, v78, v68
	v_add_f32_e32 v68, v79, v68
	v_add_f32_e32 v236, v236, v68
	v_cvt_pk_bf16_f32 v130, v76, v77
	v_cvt_pk_bf16_f32 v131, v78, v79
	v_max3_f32 v69, v69, v120, v121
	v_max3_f32 v69, v69, v122, v123
	v_max3_f32 v69, v69, v124, v125
	v_max3_f32 v69, v69, v126, v127
	s_add_u32 s30, s98, 0xffffe000
	s_addc_u32 s31, s99, -1
	s_add_i32 s18, s86, s89
	s_nop 0
	s_mov_b32 s23, m0
	s_mov_b32 m0, s18
	s_nop 0
	global_load_lds_dwordx4 v196, s[30:31]
	s_mov_b32 m0, s23
	s_add_u32 s30, s100, 0xffffc000
	s_addc_u32 s31, s101, -1
	s_lshl_b32 s18, s37, 1
	s_add_i32 s18, s18, s90
	s_mov_b32 s23, m0
	s_mov_b32 m0, s18
	s_nop 0
	global_load_lds_dwordx4 v196, s[30:31]
	s_mov_b32 m0, s23
	s_add_u32 s30, s100, 0xffffe000
	s_addc_u32 s31, s101, -1
	s_addk_i32 s18, 0x2000
	s_mov_b32 s23, m0
	s_mov_b32 m0, s18
	s_nop 0
	global_load_lds_dwordx4 v196, s[30:31]
	s_mov_b32 m0, s23
	v_max_f32_e32 v70, v96, v97
	v_max3_f32 v70, v70, v98, v99
	v_max3_f32 v70, v70, v100, v101
	v_max3_f32 v70, v70, v102, v103
	v_max3_f32 v70, v70, v104, v105
	v_max3_f32 v70, v70, v106, v107
	v_max3_f32 v70, v70, v108, v109
	v_max3_f32 v70, v70, v110, v111
	v_max_f32_e32 v68, v69, v70
	v_cmp_lt_f32_e32 vcc, s71, v68
	s_cmp_lg_u64 vcc, 0
	s_cselect_b64 s[50:51], -1, 0
	s_cbranch_vccnz .LBB0_1285

.LBB0_1280:
	s_add_i32 s18, s37, 0x2000
	s_lshl_b32 s23, s86, 1
	v_mfma_f32_32x32x16_bf16 v[80:95], v[192:195], v[156:159], v[238:253]
	v_add_u32_e32 v237, s23, v214
	ds_read_b64_tr_b16 v[180:181], v237 offset:24576
	s_cmpk_lg_i32 s37, 0x4000
	s_cselect_b32 s86, s18, 0
	v_add_f32_e32 v128, v112, v113
	v_add_f32_e32 v128, v114, v128
	v_add_f32_e32 v128, v115, v128
	v_add_f32_e32 v128, v116, v128
	v_add_f32_e32 v128, v117, v128
	v_cvt_pk_bf16_f32 v148, v112, v113
	v_cvt_pk_bf16_f32 v149, v114, v115
	ds_read_b64_tr_b16 v[182:183], v237 offset:25088
	s_waitcnt lgkmcnt(8)
	v_mfma_f32_32x32x16_bf16 v[80:95], v[184:187], v[152:155], v[80:95]
	v_add_f32_e32 v112, v118, v128
	v_add_f32_e32 v112, v119, v112
	v_add_f32_e32 v112, v120, v112
	v_add_f32_e32 v114, v121, v112
	v_cvt_pk_bf16_f32 v150, v116, v117
	v_cvt_pk_bf16_f32 v151, v118, v119
	ds_read_b64_tr_b16 v[112:113], v237 offset:28672
	s_waitcnt lgkmcnt(8)
	v_mfma_f32_32x32x16_bf16 v[80:95], v[172:175], v[144:147], v[80:95]
	v_add_f32_e32 v114, v122, v114
	v_add_f32_e32 v114, v123, v114
	v_add_f32_e32 v114, v124, v114
	v_add_f32_e32 v116, v125, v114
	v_cvt_pk_bf16_f32 v140, v120, v121
	v_cvt_pk_bf16_f32 v141, v122, v123
	ds_read_b64_tr_b16 v[114:115], v237 offset:29184
	s_waitcnt lgkmcnt(8)
	v_mfma_f32_32x32x16_bf16 v[80:95], v[164:167], v[136:139], v[80:95]
	v_add_f32_e32 v116, v126, v116
	v_add_f32_e32 v116, v127, v116
	v_add_f32_e32 v116, v96, v116
	v_add_f32_e32 v118, v97, v116
	v_cvt_pk_bf16_f32 v142, v124, v125
	v_cvt_pk_bf16_f32 v143, v126, v127
	ds_read_b64_tr_b16 v[116:117], v237 offset:32768
	s_waitcnt lgkmcnt(8)
	v_mfma_f32_32x32x16_bf16 v[64:79], v[188:191], v[156:159], v[238:253]
	v_add_f32_e32 v118, v98, v118
	v_add_f32_e32 v118, v99, v118
	v_add_f32_e32 v118, v100, v118
	v_add_f32_e32 v120, v101, v118
	v_cvt_pk_bf16_f32 v132, v96, v97
	v_cvt_pk_bf16_f32 v133, v98, v99
	ds_read_b64_tr_b16 v[118:119], v237 offset:33280
	s_waitcnt lgkmcnt(8)
	v_mfma_f32_32x32x16_bf16 v[64:79], v[176:179], v[152:155], v[64:79]
	v_add_f32_e32 v96, v102, v120
	v_add_f32_e32 v96, v103, v96
	v_add_f32_e32 v96, v104, v96
	v_add_f32_e32 v98, v105, v96
	v_cvt_pk_bf16_f32 v134, v100, v101
	v_cvt_pk_bf16_f32 v135, v102, v103
	ds_read_b64_tr_b16 v[96:97], v237 offset:36864
	s_waitcnt lgkmcnt(8)
	v_mfma_f32_32x32x16_bf16 v[64:79], v[168:171], v[144:147], v[64:79]
	v_add_f32_e32 v98, v106, v98
	v_add_f32_e32 v98, v107, v98
	v_add_f32_e32 v98, v108, v98
	v_add_f32_e32 v100, v109, v98
	v_cvt_pk_bf16_f32 v128, v104, v105
	v_cvt_pk_bf16_f32 v129, v106, v107
	v_max_f32_e32 v101, v80, v81
	v_max3_f32 v101, v101, v82, v83
	v_max3_f32 v101, v101, v84, v85
	v_max3_f32 v101, v101, v86, v87
	ds_read_b64_tr_b16 v[98:99], v237 offset:37376
	s_waitcnt lgkmcnt(8)
	v_mfma_f32_32x32x16_bf16 v[64:79], v[160:163], v[136:139], v[64:79]
	v_add_f32_e32 v100, v110, v100
	v_add_f32_e32 v100, v111, v100
	v_add_f32_e32 v236, v236, v100
	v_cvt_pk_bf16_f32 v130, v108, v109
	v_cvt_pk_bf16_f32 v131, v110, v111
	v_max3_f32 v101, v101, v88, v89
	v_max3_f32 v101, v101, v90, v91
	v_max3_f32 v101, v101, v92, v93
	v_max3_f32 v101, v101, v94, v95
	s_add_i32 s18, s37, s89
	s_mov_b32 s23, m0
	s_mov_b32 m0, s18
	s_nop 0
	global_load_lds_dwordx4 v196, s[98:99]
	s_mov_b32 m0, s23
	s_lshl_b32 s18, s86, 1
	s_add_i32 s18, s18, s90
	s_mov_b32 s23, m0
	s_mov_b32 m0, s18
	s_nop 0
	global_load_lds_dwordx4 v196, s[100:101]
	s_mov_b32 m0, s23
	s_add_u32 s30, s100, 0x2000
	s_addc_u32 s31, s101, 0
	s_addk_i32 s18, 0x2000
	s_mov_b32 s23, m0
	s_mov_b32 m0, s18
	s_nop 0
	global_load_lds_dwordx4 v196, s[30:31]
	s_mov_b32 m0, s23
	v_max_f32_e32 v102, v64, v65
	v_max3_f32 v102, v102, v66, v67
	v_max3_f32 v102, v102, v68, v69
	v_max3_f32 v102, v102, v70, v71
	v_max3_f32 v102, v102, v72, v73
	v_max3_f32 v102, v102, v74, v75
	v_max3_f32 v102, v102, v76, v77
	v_max3_f32 v102, v102, v78, v79
	v_max_f32_e32 v100, v101, v102
	v_cmp_lt_f32_e32 vcc, s71, v100
	s_cmp_lg_u64 vcc, 0
	s_cselect_b64 s[50:51], -1, 0
	s_cbranch_vccnz .LBB0_1288
